# attention: next unit's Q-fragment loads issued with lanes relabelled so each lane quad reads 64 contiguous bytes, relabelling undone with ds_bpermute at the copy; on top of the previous changes
# speedup vs baseline: 1.0092x; 1.0092x over previous
; #define LAS __attribute__((address_space(3)))
; __global__ void __launch_bounds__(NWAVES * 64, 2) hybrid_fwd(Args a) {
;     extern __shared__ __attribute__((aligned(16))) unsigned char lds_raw[];
;     cg::grid_group grid = cg::this_grid();
;     LAS unsigned char* lds = (LAS unsigned char*)lds_raw;
;     const int G = gridDim.x, bx = blockIdx.x, NGW = G * NWAVES;
;     const int wave_k = __builtin_amdgcn_readfirstlane((int)threadIdx.x >> 6);
;     ...
;     unsigned char* ws = a.ws;
;     ...
;     unsigned* barw = (unsigned*)(ws + WS_BAR);
;     if (bx == 0) for (int i = threadIdx.x; i < XCD_BAR_WORDS; i += NWAVES * 64) barw[i] = 0u;
_Z10hybrid_fwd4Args:
	v_mbcnt_lo_u32_b32 v255, -1, 0
	v_mbcnt_hi_u32_b32 v255, -1, v255
	v_and_b32_e32 v254, 3, v255
	v_lshrrev_b32_e32 v255, 2, v255
	v_lshl_add_u32 v255, v254, 4, v255
	v_lshlrev_b32_e32 v255, 2, v255
	v_mbcnt_lo_u32_b32 v254, -1, 0
	v_mbcnt_hi_u32_b32 v254, -1, v254
	v_and_b32_e32 v253, 15, v254
	v_lshrrev_b32_e32 v254, 4, v254
	v_lshl_add_u32 v254, v253, 2, v254
	v_lshlrev_b32_e32 v254, 2, v254
	s_mov_b32 s94, s2
	s_add_u32 s2, s0, 0x70
	s_addc_u32 s3, s1, 0
	s_load_dwordx4 s[16:19], s[0:1], 0x60
	s_load_dwordx8 s[20:27], s[0:1], 0x40
	v_writelane_b32 v252, s2, 0
	s_load_dwordx2 s[6:7], s[0:1], 0x70
	v_and_b32_e32 v18, 0x3ff, v0
	v_writelane_b32 v252, s3, 1
	s_load_dword s2, s[0:1], 0x78
	v_readfirstlane_b32 s4, v18
	s_waitcnt lgkmcnt(0)
	v_writelane_b32 v252, s2, 2
	s_add_u32 s2, s18, 0x1fd00000
	s_addc_u32 s3, s19, 0
	v_writelane_b32 v252, s2, 3
	s_cmp_lg_u32 s94, 0
	s_nop 0
	v_writelane_b32 v252, s3, 4
	s_mov_b32 s2, 0
	s_cbranch_scc1 .LBB0_8
	v_sub_u32_e32 v1, 0xd7f, v18
	v_lshrrev_b32_e32 v2, 9, v1
	v_add_u32_e32 v1, 2, v2
	v_add_u32_e32 v19, 0x200, v18
	s_mov_b32 s14, s4
	v_and_b32_e32 v3, 14, v1
	v_mov_b32_e32 v1, v2
	s_mov_b64 s[8:9], 0
	s_mov_b32 s3, 1
	v_mov_b32_e32 v5, 0
	s_mov_b32 s10, s2
	v_mov_b64_e32 v[6:7], v[18:19]
	s_branch .LBB0_3

; #define LSE WSPTR(float, WS_LSE)
; __global__ void __launch_bounds__(NWAVES * 64, 2) hybrid_fwd(Args a) {
;     ...
;             for (int idx = 0; idx < 12; ++idx) {
;                 attn_stage(lds, P, cu, tid);
;                 bf16x8 qf[4] = {P.q[0], P.q[1], P.q[2], P.q[3]};
;                 __syncthreads();
;                 const AttnUid u = cu;
;                 if (idx + 1 < 12) { cu = attn_decode_chain(vx, vr, idx + 1); attn_load(P, Z, cu, tid, wave, lane); }
;                 attn_compute(lds, qf, u, ON, LSE, wave, lane);
;                 __syncthreads();
;             }
.LBB0_220:
	s_or_b64 exec, exec, s[0:1]
	s_addk_i32 s24, 0x80
	s_add_i32 s33, s33, 1
	s_add_i32 s26, s26, 8
	s_waitcnt vmcnt(4)
	ds_bpermute_b32 v98, v254, v82
	ds_bpermute_b32 v99, v254, v83
	ds_bpermute_b32 v90, v254, v74
	ds_bpermute_b32 v91, v254, v75
	ds_bpermute_b32 v94, v254, v70
	ds_bpermute_b32 v95, v254, v71
	ds_bpermute_b32 v86, v254, v78
	ds_bpermute_b32 v87, v254, v79
	v_readlane_b32 s94, v252, 39
	s_cmpk_eq_i32 s24, 0x680
	ds_bpermute_b32 v96, v254, v80
	ds_bpermute_b32 v97, v254, v81
	ds_bpermute_b32 v88, v254, v72
	ds_bpermute_b32 v89, v254, v73
	ds_bpermute_b32 v92, v254, v68
	ds_bpermute_b32 v93, v254, v69
	ds_bpermute_b32 v84, v254, v76
	ds_bpermute_b32 v85, v254, v77
	s_mov_b32 s35, s40
	s_mov_b32 s41, s27
	s_mov_b32 s29, s36
	s_mov_b32 s39, s31
	s_mov_b32 s37, s28
	s_mov_b32 s34, s38
	v_readlane_b32 s95, v252, 40
	v_readlane_b32 s50, v252, 33
	s_waitcnt lgkmcnt(0)
	s_barrier
	v_readlane_b32 s51, v252, 34
	s_cbranch_scc1 .LBB0_262

; __device__ __forceinline__ void attn_load(AttnPre& P, const bf16* Z, const AttnUid& u, int tid, int wave, int lane) {
;     ...
;     const int fr = lane & 15, fq = lane >> 4;
;     const int qsub = u.n * 128 + 16 * wave + fr;
;     const bf16* qp = Zb + (size_t)(qsub * u.d + u.r) * INW + 2048 + h * HD + 8 * fq;
; #pragma unroll
;     for (int ks = 0; ks < 4; ++ks) P.q[ks] = *(const bf16x8*)(qp + 32 * ks);
.LBB0_257:
	s_or_b64 exec, exec, s[18:19]
	v_add_u32_e32 v1, s40, v166
	v_lshlrev_b32_e32 v1, s31, v1
	v_add_u32_e32 v1, s36, v1
	v_mov_b64_e32 v[2:3], s[0:1]
	v_mad_i64_i32 v[2:3], s[0:1], v1, s52, v[2:3]
	v_lshl_add_u64 v[2:3], v[2:3], 0, s[54:55]
	v_lshl_add_u64 v[2:3], v[130:131], 1, v[2:3]
	s_mov_b64 s[0:1], 0x1000
	v_lshl_add_u64 v[80:81], v[2:3], 0, s[0:1]
	v_add_co_u32_e32 v2, vcc, 0x1000, v2
	s_and_b32 s40, s24, 0x80
	s_nop 0
	v_addc_co_u32_e32 v3, vcc, 0, v3, vcc
	v_mbcnt_lo_u32_b32 v100, -1, 0
	v_mbcnt_hi_u32_b32 v100, -1, v100
	v_lshrrev_b32_e32 v101, 2, v100
	v_and_b32_e32 v104, 15, v100
	v_sub_u32_e32 v101, v101, v104
	v_lshlrev_b32_e32 v101, s31, v101
	v_mul_i32_i24_e32 v101, s52, v101
	v_and_b32_e32 v104, 3, v100
	v_lshrrev_b32_e32 v105, 4, v100
	v_sub_u32_e32 v104, v104, v105
	v_lshl_add_u32 v102, v104, 4, v101
	v_ashrrev_i32_e32 v103, 31, v102
	v_lshl_add_u64 v[80:81], v[80:81], 0, v[102:103]
	v_lshl_add_u64 v[2:3], v[2:3], 0, v[102:103]
	global_load_dwordx4 v[68:71], v[80:81], off offset:64
	global_load_dwordx4 v[72:75], v[80:81], off offset:128
	global_load_dwordx4 v[76:79], v[2:3], off
	s_nop 0
	global_load_dwordx4 v[80:83], v[80:81], off offset:192
